# B-unit MFMA stage: all 16 spatial-weight loads and 8 LDS fragment reads issued up front, one wait, 8 back-to-back MFMAs (was a load-wait-MFMA chain per k-step)
# speedup vs baseline: 1.0176x; 1.0002x over previous
; #define LAS __attribute__((address_space(3)))
; __device__ __forceinline__ unsigned cvt_pk_bf16(float lo, float hi) { const f32x2 v = {lo, hi}; const bf16x2_t b = __builtin_convertvector(v, bf16x2_t); return __builtin_bit_cast(unsigned, b); }
; __device__ __forceinline__ void bmix_unit(LAS unsigned char* lds, const bf16_t* U, const bf16_t* VG, const float* gv  , const float* ws  , const float* bs  ,
;                                           int ci, int g, bf16_t* Y) {
;     ...
; #pragma unroll
;     for (int i = 0; i < 2; ++i) {
;         const int idx = tid + i * NTHREADS; const int q = idx >> 3, c8 = idx & 7;
;         const u32x4 w = *(const u32x4*)(VG + (size_t)(r0 + q) * 256 + g * 64 + c8 * 8); const float rs = rstd[q];
; #pragma unroll
;         for (int e = 0; e < 4; ++e) {
;             const float lo = __uint_as_float(w[e] << 16) * rs * gv[g * 64 + c8 * 8 + 2 * e], hi2 = __uint_as_float(w[e] & 0xffff0000u) * rs * gv[g * 64 + c8 * 8 + 2 * e + 1];
;             const unsigned pk = cvt_pk_bf16(lo, hi2);
;             vnT[(c8 * 8 + 2 * e) * 136 + q] = (bf16_t)(pk & 0xffffu); vnT[(c8 * 8 + 2 * e + 1) * 136 + q] = (bf16_t)(pk >> 16);
;         }
;     }
;     __syncthreads();
;     const int pblk = wid & 3, cblk = wid >> 2;
;     f32x16 acc;
; #pragma unroll
;     for (int r = 0; r < 16; ++r) acc[r] = 0.f;
;     const float* wrow = ws + ((size_t)g * 128 + pblk * 32 + r32) * 128 + hi * 8;
; #pragma unroll
;     for (int ks = 0; ks < 8; ++ks) {
;         const f32x4 a0 = *(const f32x4*)(wrow + ks * 16), a1 = *(const f32x4*)(wrow + ks * 16 + 4);
;         u32x4 aw; aw.x = cvt_pk_bf16(a0[0], a0[1]); aw.y = cvt_pk_bf16(a0[2], a0[3]); aw.z = cvt_pk_bf16(a1[0], a1[1]); aw.w = cvt_pk_bf16(a1[2], a1[3]);
;         const bf16x8 bfr = *(const LAS bf16x8*)(vnT + (cblk * 32 + r32) * 136 + ks * 16 + hi * 8);
;         acc = __builtin_amdgcn_mfma_f32_32x32x16_bf16(__builtin_bit_cast(bf16x8, aw), bfr, acc, 0, 0, 0);
;     }
.LBB0_592:
	s_or_b64 exec, exec, s[0:1]
	s_and_b32 s0, s56, 3
	s_lshl_b32 s1, s0, 6
	s_lshl_b32 s0, s0, 7
	v_readlane_b32 s8, v254, 31
	v_lshlrev_b32_e32 v0, 3, v16
	v_ashrrev_i32_e32 v19, 3, v16
	v_readlane_b32 s9, v254, 32
	s_add_u32 s8, s8, s0
	v_and_b32_e32 v15, 56, v0
	v_add_u32_e32 v0, s6, v19
	s_addc_u32 s9, s9, 0
	v_lshlrev_b32_e32 v194, 1, v15
	s_waitcnt lgkmcnt(0)
	v_ashrrev_i32_e32 v1, 31, v0
	v_lshl_add_u64 v[12:13], s[8:9], 0, v[194:195]
	v_lshlrev_b64 v[0:1], 9, v[0:1]
	v_lshl_add_u64 v[0:1], v[12:13], 0, v[0:1]
	s_barrier
	global_load_dwordx4 v[8:11], v[0:1], off
	v_lshl_add_u32 v0, v19, 2, 0
	ds_read_b32 v14, v0
	v_or_b32_e32 v2, s1, v15
	v_lshlrev_b32_e32 v4, 2, v2
	s_movk_i32 s10, 0x110
	s_lshr_b32 s8, s7, 1
	s_and_b32 s8, s8, 0x60
	v_and_b32_e32 v17, 31, v16
	s_or_b32 s9, s0, s8
	v_readlane_b32 s12, v255, 27
	v_bfe_u32 v18, v16, 5, 1
	v_readlane_b32 s13, v255, 28
	s_waitcnt vmcnt(0)
	v_lshlrev_b32_e32 v0, 16, v8
	v_and_b32_e32 v1, 0xffff0000, v8
	s_waitcnt lgkmcnt(0)
	v_mul_f32_e32 v20, v14, v0
	v_mul_f32_e32 v21, v14, v1
	global_load_dwordx4 v[0:3], v4, s[26:27] offset:16
	s_nop 0
	global_load_dwordx4 v[4:7], v4, s[26:27]
	s_waitcnt vmcnt(0)
	v_mul_f32_e32 v20, v4, v20
	v_mul_f32_e32 v21, v5, v21
	s_nop 0
	v_cvt_pk_bf16_f32 v8, v20, v21
	v_mad_u32_u24 v20, v15, s10, 0
	v_lshl_add_u32 v15, v19, 1, v20
	ds_write_b16 v15, v8 offset:512
	ds_write_b16_d16_hi v15, v8 offset:784
	v_lshlrev_b32_e32 v8, 16, v9
	v_and_b32_e32 v9, 0xffff0000, v9
	v_mul_f32_e32 v8, v14, v8
	v_mul_f32_e32 v9, v14, v9
	v_mul_f32_e32 v8, v8, v6
	v_mul_f32_e32 v9, v9, v7
	s_nop 0
	v_cvt_pk_bf16_f32 v8, v8, v9
	ds_write_b16 v15, v8 offset:1056
	ds_write_b16_d16_hi v15, v8 offset:1328
	v_lshlrev_b32_e32 v8, 16, v10
	v_and_b32_e32 v9, 0xffff0000, v10
	v_mul_f32_e32 v8, v14, v8
	v_mul_f32_e32 v9, v14, v9
	v_mul_f32_e32 v8, v8, v0
	v_mul_f32_e32 v9, v9, v1
	s_nop 0
	v_cvt_pk_bf16_f32 v8, v8, v9
	ds_write_b16 v15, v8 offset:1600
	ds_write_b16_d16_hi v15, v8 offset:1872
	v_lshlrev_b32_e32 v8, 16, v11
	v_and_b32_e32 v9, 0xffff0000, v11
	v_mul_f32_e32 v8, v14, v8
	v_mul_f32_e32 v9, v14, v9
	v_mul_f32_e32 v8, v8, v2
	v_mul_f32_e32 v9, v9, v3
	s_nop 0
	v_cvt_pk_bf16_f32 v8, v8, v9
	ds_write_b16 v15, v8 offset:2144
	ds_write_b16_d16_hi v15, v8 offset:2416
	v_add_u32_e32 v8, 0x200, v16
	v_ashrrev_i32_e32 v19, 3, v8
	v_add_u32_e32 v8, s6, v19
	v_ashrrev_i32_e32 v9, 31, v8
	v_lshlrev_b64 v[8:9], 9, v[8:9]
	v_lshl_add_u64 v[8:9], v[12:13], 0, v[8:9]
	global_load_dwordx4 v[8:11], v[8:9], off
	v_lshl_add_u32 v12, v19, 2, 0
	ds_read_b32 v12, v12
	s_waitcnt vmcnt(0)
	v_lshlrev_b32_e32 v14, 16, v8
	v_and_b32_e32 v15, 0xffff0000, v8
	s_waitcnt lgkmcnt(0)
	v_mul_f32_e32 v14, v12, v14
	v_mul_f32_e32 v15, v12, v15
	v_mul_f32_e32 v4, v4, v14
	v_mul_f32_e32 v5, v5, v15
	v_lshl_add_u32 v8, v19, 1, v20
	v_cvt_pk_bf16_f32 v4, v4, v5
	ds_write_b16 v8, v4 offset:512
	ds_write_b16_d16_hi v8, v4 offset:784
	v_lshlrev_b32_e32 v4, 16, v9
	v_and_b32_e32 v5, 0xffff0000, v9
	v_mul_f32_e32 v4, v12, v4
	v_mul_f32_e32 v5, v12, v5
	v_mul_f32_e32 v4, v6, v4
	v_mul_f32_e32 v5, v7, v5
	s_nop 0
	v_cvt_pk_bf16_f32 v4, v4, v5
	ds_write_b16 v8, v4 offset:1056
	ds_write_b16_d16_hi v8, v4 offset:1328
	v_lshlrev_b32_e32 v4, 16, v10
	v_and_b32_e32 v5, 0xffff0000, v10
	v_mul_f32_e32 v4, v12, v4
	v_mul_f32_e32 v5, v12, v5
	v_mul_f32_e32 v0, v0, v4
	v_mul_f32_e32 v1, v1, v5
	s_nop 0
	v_cvt_pk_bf16_f32 v0, v0, v1
	ds_write_b16 v8, v0 offset:1600
	ds_write_b16_d16_hi v8, v0 offset:1872
	v_lshlrev_b32_e32 v0, 16, v11
	v_and_b32_e32 v1, 0xffff0000, v11
	v_mul_f32_e32 v0, v12, v0
	v_mul_f32_e32 v1, v12, v1
	v_mul_f32_e32 v0, v2, v0
	v_mul_f32_e32 v1, v3, v1
	s_nop 0
	v_cvt_pk_bf16_f32 v0, v0, v1
	ds_write_b16 v8, v0 offset:2144
	ds_write_b16_d16_hi v8, v0 offset:2416
	v_or_b32_e32 v0, s9, v17
	v_lshlrev_b32_e32 v194, 9, v0
	v_lshl_add_u64 v[0:1], s[12:13], 0, v[194:195]
	v_lshlrev_b32_e32 v194, 5, v18
	s_ashr_i32 s9, s7, 3
	v_lshl_add_u64 v[32:33], v[0:1], 0, v[194:195]
	s_and_b32 s7, s9, 0xffffffe0
	v_mov_b32_e32 v0, s9
	s_movk_i32 s9, 0xffe0
	v_bfi_b32 v0, s9, v0, v16
	v_mul_lo_u32 v0, v0, s10
	v_lshlrev_b32_e32 v1, 4, v18
	s_waitcnt lgkmcnt(0)
	s_barrier
	v_add3_u32 v16, 0, v0, v1
	global_load_dwordx4 v[60:63], v[32:33], off
	global_load_dwordx4 v[64:67], v[32:33], off offset:16
	global_load_dwordx4 v[68:71], v[32:33], off offset:64
	global_load_dwordx4 v[72:75], v[32:33], off offset:80
	global_load_dwordx4 v[76:79], v[32:33], off offset:128
	global_load_dwordx4 v[80:83], v[32:33], off offset:144
	global_load_dwordx4 v[84:87], v[32:33], off offset:192
	global_load_dwordx4 v[88:91], v[32:33], off offset:208
	global_load_dwordx4 v[92:95], v[32:33], off offset:256
	global_load_dwordx4 v[96:99], v[32:33], off offset:272
	global_load_dwordx4 v[100:103], v[32:33], off offset:320
	global_load_dwordx4 v[104:107], v[32:33], off offset:336
	global_load_dwordx4 v[108:111], v[32:33], off offset:384
	global_load_dwordx4 v[112:115], v[32:33], off offset:400
	global_load_dwordx4 v[116:119], v[32:33], off offset:448
	global_load_dwordx4 v[120:123], v[32:33], off offset:464
	s_add_i32 s7, s7, s1
	ds_read_b128 v[124:127], v16 offset:512
	ds_read_b128 v[128:131], v16 offset:544
	ds_read_b128 v[132:135], v16 offset:576
	ds_read_b128 v[136:139], v16 offset:608
	ds_read_b128 v[140:143], v16 offset:640
	ds_read_b128 v[144:147], v16 offset:672
	ds_read_b128 v[148:151], v16 offset:704
	ds_read_b128 v[152:155], v16 offset:736
	v_or_b32_e32 v16, s7, v17
	s_waitcnt vmcnt(0) lgkmcnt(0)
; #define LAS __attribute__((address_space(3)))
; __device__ __forceinline__ unsigned cvt_pk_bf16(float lo, float hi) { const f32x2 v = {lo, hi}; const bf16x2_t b = __builtin_convertvector(v, bf16x2_t); return __builtin_bit_cast(unsigned, b); }
; __device__ __forceinline__ float bf2f(bf16_t v) { return __uint_as_float(((unsigned)v) << 16); }
; __device__ __forceinline__ int crow(int r, int hi) { return (r & 3) + 8 * (r >> 2) + 4 * hi; }
; __device__ __forceinline__ void bmix_unit(LAS unsigned char* lds, const bf16_t* U, const bf16_t* VG, const float* gv  , const float* ws  , const float* bs  ,
;                                           int ci, int g, bf16_t* Y) {
;     ...
;     const float* wrow = ws + ((size_t)g * 128 + pblk * 32 + r32) * 128 + hi * 8;
; #pragma unroll
;     for (int ks = 0; ks < 8; ++ks) {
;         const f32x4 a0 = *(const f32x4*)(wrow + ks * 16), a1 = *(const f32x4*)(wrow + ks * 16 + 4);
;         u32x4 aw; aw.x = cvt_pk_bf16(a0[0], a0[1]); aw.y = cvt_pk_bf16(a0[2], a0[3]); aw.z = cvt_pk_bf16(a1[0], a1[1]); aw.w = cvt_pk_bf16(a1[2], a1[3]);
;         const bf16x8 bfr = *(const LAS bf16x8*)(vnT + (cblk * 32 + r32) * 136 + ks * 16 + hi * 8);
;         acc = __builtin_amdgcn_mfma_f32_32x32x16_bf16(__builtin_bit_cast(bf16x8, aw), bfr, acc, 0, 0, 0);
;     }
; #pragma unroll
;     for (int r = 0; r < 16; ++r) {
;         const int p = pblk * 32 + crow(r, hi); const int col = g * 64 + cblk * 32 + r32;
;         const float mixed = acc[r] + bs[g * 128 + p];
;         const float uu = bf2f(U[(size_t)(r0 + p) * 256 + col]);
;         Y[(size_t)(r0 + p) * DM + 384 + col] = (bf16_t)(cvt_pk_bf16(uu * mixed, 0.f) & 0xffffu);
;     }
	v_cvt_pk_bf16_f32 v156, v60, v61
	v_cvt_pk_bf16_f32 v157, v62, v63
	v_cvt_pk_bf16_f32 v158, v64, v65
	v_cvt_pk_bf16_f32 v159, v66, v67
	s_nop 1
	v_mfma_f32_32x32x16_bf16 v[0:15], v[156:159], v[124:127], 0
	v_cvt_pk_bf16_f32 v160, v68, v69
	v_cvt_pk_bf16_f32 v161, v70, v71
	v_cvt_pk_bf16_f32 v162, v72, v73
	v_cvt_pk_bf16_f32 v163, v74, v75
	s_nop 1
	v_mfma_f32_32x32x16_bf16 v[0:15], v[160:163], v[128:131], v[0:15]
	v_cvt_pk_bf16_f32 v156, v76, v77
	v_cvt_pk_bf16_f32 v157, v78, v79
	v_cvt_pk_bf16_f32 v158, v80, v81
	v_cvt_pk_bf16_f32 v159, v82, v83
	s_nop 1
	v_mfma_f32_32x32x16_bf16 v[0:15], v[156:159], v[132:135], v[0:15]
	v_cvt_pk_bf16_f32 v160, v84, v85
	v_cvt_pk_bf16_f32 v161, v86, v87
	v_cvt_pk_bf16_f32 v162, v88, v89
	v_cvt_pk_bf16_f32 v163, v90, v91
	s_nop 1
	v_mfma_f32_32x32x16_bf16 v[0:15], v[160:163], v[136:139], v[0:15]
	v_cvt_pk_bf16_f32 v156, v92, v93
	v_cvt_pk_bf16_f32 v157, v94, v95
	v_cvt_pk_bf16_f32 v158, v96, v97
	v_cvt_pk_bf16_f32 v159, v98, v99
	s_nop 1
	v_mfma_f32_32x32x16_bf16 v[0:15], v[156:159], v[140:143], v[0:15]
	v_cvt_pk_bf16_f32 v160, v100, v101
	v_cvt_pk_bf16_f32 v161, v102, v103
	v_cvt_pk_bf16_f32 v162, v104, v105
	v_cvt_pk_bf16_f32 v163, v106, v107
	s_nop 1
	v_mfma_f32_32x32x16_bf16 v[0:15], v[160:163], v[144:147], v[0:15]
	v_cvt_pk_bf16_f32 v156, v108, v109
	v_cvt_pk_bf16_f32 v157, v110, v111
	v_cvt_pk_bf16_f32 v158, v112, v113
	v_cvt_pk_bf16_f32 v159, v114, v115
	s_nop 1
	v_mfma_f32_32x32x16_bf16 v[0:15], v[156:159], v[148:151], v[0:15]
	v_cvt_pk_bf16_f32 v160, v116, v117
	v_cvt_pk_bf16_f32 v161, v118, v119
	v_cvt_pk_bf16_f32 v162, v120, v121
	v_cvt_pk_bf16_f32 v163, v122, v123
	s_nop 1
	v_mfma_f32_32x32x16_bf16 v[0:15], v[160:163], v[152:155], v[0:15]
	v_lshl_or_b32 v25, v18, 2, s8
	v_ashrrev_i32_e32 v17, 31, v16
	v_lshlrev_b64 v[20:21], 1, v[16:17]
	v_or_b32_e32 v16, s0, v25
	v_readlane_b32 s0, v255, 29
	v_lshlrev_b32_e32 v24, 2, v16
	v_readlane_b32 s1, v255, 30
	v_readlane_b32 s8, v254, 29
	v_readlane_b32 s9, v254, 30
	v_or_b32_e32 v194, s6, v25
	v_mov_b32_e32 v79, 0
	v_lshl_add_u64 v[22:23], s[8:9], 0, v[20:21]
	global_load_dwordx4 v[60:63], v24, s[0:1]
	global_load_dwordx4 v[64:67], v24, s[0:1] offset:32
	global_load_dwordx4 v[68:71], v24, s[0:1] offset:64
	global_load_dwordx4 v[72:75], v24, s[0:1] offset:96
	v_lshl_add_u64 v[76:77], s[86:87], 0, v[20:21]
	v_mov_b32_e32 v78, v194
	v_lshlrev_b64 v[80:81], 9, v[78:79]
	v_lshlrev_b64 v[82:83], 11, v[78:79]
	v_lshl_add_u64 v[80:81], v[22:23], 0, v[80:81]
	v_lshl_add_u64 v[100:101], v[76:77], 0, v[82:83]
	global_load_ushort v84, v[80:81], off
	v_or_b32_e32 v78, 1, v194
	v_lshlrev_b64 v[80:81], 9, v[78:79]
	v_lshlrev_b64 v[82:83], 11, v[78:79]
	v_lshl_add_u64 v[80:81], v[22:23], 0, v[80:81]
	v_lshl_add_u64 v[102:103], v[76:77], 0, v[82:83]
	global_load_ushort v85, v[80:81], off
	v_or_b32_e32 v78, 2, v194
	v_lshlrev_b64 v[80:81], 9, v[78:79]
	v_lshlrev_b64 v[82:83], 11, v[78:79]
	v_lshl_add_u64 v[80:81], v[22:23], 0, v[80:81]
	v_lshl_add_u64 v[104:105], v[76:77], 0, v[82:83]
	global_load_ushort v86, v[80:81], off
	v_or_b32_e32 v78, 3, v194
	v_lshlrev_b64 v[80:81], 9, v[78:79]
	v_lshlrev_b64 v[82:83], 11, v[78:79]
	v_lshl_add_u64 v[80:81], v[22:23], 0, v[80:81]
	v_lshl_add_u64 v[106:107], v[76:77], 0, v[82:83]
	global_load_ushort v87, v[80:81], off
	v_or_b32_e32 v78, 8, v194
	v_lshlrev_b64 v[80:81], 9, v[78:79]
	v_lshlrev_b64 v[82:83], 11, v[78:79]
	v_lshl_add_u64 v[80:81], v[22:23], 0, v[80:81]
	v_lshl_add_u64 v[108:109], v[76:77], 0, v[82:83]
	global_load_ushort v88, v[80:81], off
	v_or_b32_e32 v78, 9, v194
	v_lshlrev_b64 v[80:81], 9, v[78:79]
	v_lshlrev_b64 v[82:83], 11, v[78:79]
	v_lshl_add_u64 v[80:81], v[22:23], 0, v[80:81]
	v_lshl_add_u64 v[110:111], v[76:77], 0, v[82:83]
	global_load_ushort v89, v[80:81], off
	v_or_b32_e32 v78, 10, v194
	v_lshlrev_b64 v[80:81], 9, v[78:79]
	v_lshlrev_b64 v[82:83], 11, v[78:79]
	v_lshl_add_u64 v[80:81], v[22:23], 0, v[80:81]
	v_lshl_add_u64 v[112:113], v[76:77], 0, v[82:83]
	global_load_ushort v90, v[80:81], off
	v_or_b32_e32 v78, 11, v194
	v_lshlrev_b64 v[80:81], 9, v[78:79]
	v_lshlrev_b64 v[82:83], 11, v[78:79]
	v_lshl_add_u64 v[80:81], v[22:23], 0, v[80:81]
	v_lshl_add_u64 v[114:115], v[76:77], 0, v[82:83]
	global_load_ushort v91, v[80:81], off
	v_or_b32_e32 v78, 16, v194
	v_lshlrev_b64 v[80:81], 9, v[78:79]
	v_lshlrev_b64 v[82:83], 11, v[78:79]
	v_lshl_add_u64 v[80:81], v[22:23], 0, v[80:81]
	v_lshl_add_u64 v[116:117], v[76:77], 0, v[82:83]
	global_load_ushort v92, v[80:81], off
	v_or_b32_e32 v78, 17, v194
	v_lshlrev_b64 v[80:81], 9, v[78:79]
	v_lshlrev_b64 v[82:83], 11, v[78:79]
	v_lshl_add_u64 v[80:81], v[22:23], 0, v[80:81]
	v_lshl_add_u64 v[118:119], v[76:77], 0, v[82:83]
	global_load_ushort v93, v[80:81], off
	v_or_b32_e32 v78, 18, v194
	v_lshlrev_b64 v[80:81], 9, v[78:79]
	v_lshlrev_b64 v[82:83], 11, v[78:79]
	v_lshl_add_u64 v[80:81], v[22:23], 0, v[80:81]
	v_lshl_add_u64 v[120:121], v[76:77], 0, v[82:83]
	global_load_ushort v94, v[80:81], off
	v_or_b32_e32 v78, 19, v194
	v_lshlrev_b64 v[80:81], 9, v[78:79]
	v_lshlrev_b64 v[82:83], 11, v[78:79]
	v_lshl_add_u64 v[80:81], v[22:23], 0, v[80:81]
	v_lshl_add_u64 v[122:123], v[76:77], 0, v[82:83]
	global_load_ushort v95, v[80:81], off
	v_or_b32_e32 v78, 24, v194
	v_lshlrev_b64 v[80:81], 9, v[78:79]
	v_lshlrev_b64 v[82:83], 11, v[78:79]
	v_lshl_add_u64 v[80:81], v[22:23], 0, v[80:81]
	v_lshl_add_u64 v[124:125], v[76:77], 0, v[82:83]
	global_load_ushort v96, v[80:81], off
	v_or_b32_e32 v78, 25, v194
	v_lshlrev_b64 v[80:81], 9, v[78:79]
	v_lshlrev_b64 v[82:83], 11, v[78:79]
	v_lshl_add_u64 v[80:81], v[22:23], 0, v[80:81]
	v_lshl_add_u64 v[126:127], v[76:77], 0, v[82:83]
	global_load_ushort v97, v[80:81], off
	v_or_b32_e32 v78, 26, v194
	v_lshlrev_b64 v[80:81], 9, v[78:79]
	v_lshlrev_b64 v[82:83], 11, v[78:79]
	v_lshl_add_u64 v[80:81], v[22:23], 0, v[80:81]
	v_lshl_add_u64 v[128:129], v[76:77], 0, v[82:83]
	global_load_ushort v98, v[80:81], off
	v_or_b32_e32 v78, 27, v194
	v_lshlrev_b64 v[80:81], 9, v[78:79]
	v_lshlrev_b64 v[82:83], 11, v[78:79]
	v_lshl_add_u64 v[80:81], v[22:23], 0, v[80:81]
	v_lshl_add_u64 v[130:131], v[76:77], 0, v[82:83]
	global_load_ushort v99, v[80:81], off
	s_waitcnt vmcnt(0)
; __device__ __forceinline__ unsigned cvt_pk_bf16(float lo, float hi) { const f32x2 v = {lo, hi}; const bf16x2_t b = __builtin_convertvector(v, bf16x2_t); return __builtin_bit_cast(unsigned, b); }
; __device__ __forceinline__ float bf2f(bf16_t v) { return __uint_as_float(((unsigned)v) << 16); }
; __device__ __forceinline__ int crow(int r, int hi) { return (r & 3) + 8 * (r >> 2) + 4 * hi; }
; __device__ __forceinline__ void bmix_unit(LAS unsigned char* lds, const bf16_t* U, const bf16_t* VG, const float* gv  , const float* ws  , const float* bs  ,
;                                           int ci, int g, bf16_t* Y) {
;     ...
;     for (int r = 0; r < 16; ++r) {
;         const int p = pblk * 32 + crow(r, hi); const int col = g * 64 + cblk * 32 + r32;
;         const float mixed = acc[r] + bs[g * 128 + p];
;         const float uu = bf2f(U[(size_t)(r0 + p) * 256 + col]);
;         Y[(size_t)(r0 + p) * DM + 384 + col] = (bf16_t)(cvt_pk_bf16(uu * mixed, 0.f) & 0xffffu);
;     }
;     __syncthreads();
	v_add_f32_e32 v132, v0, v60
	v_lshlrev_b32_e32 v84, 16, v84
	v_mul_f32_e32 v132, v132, v84
	v_cvt_pk_bf16_f32 v132, v132, v132
	global_store_short v[100:101], v132, off offset:768
	v_add_f32_e32 v133, v1, v61
	v_lshlrev_b32_e32 v85, 16, v85
	v_mul_f32_e32 v133, v133, v85
	v_cvt_pk_bf16_f32 v133, v133, v133
	global_store_short v[102:103], v133, off offset:768
	v_add_f32_e32 v134, v2, v62
	v_lshlrev_b32_e32 v86, 16, v86
	v_mul_f32_e32 v134, v134, v86
	v_cvt_pk_bf16_f32 v134, v134, v134
	global_store_short v[104:105], v134, off offset:768
	v_add_f32_e32 v135, v3, v63
	v_lshlrev_b32_e32 v87, 16, v87
	v_mul_f32_e32 v135, v135, v87
	v_cvt_pk_bf16_f32 v135, v135, v135
	global_store_short v[106:107], v135, off offset:768
	v_add_f32_e32 v136, v4, v64
	v_lshlrev_b32_e32 v88, 16, v88
	v_mul_f32_e32 v136, v136, v88
	v_cvt_pk_bf16_f32 v136, v136, v136
	global_store_short v[108:109], v136, off offset:768
	v_add_f32_e32 v137, v5, v65
	v_lshlrev_b32_e32 v89, 16, v89
	v_mul_f32_e32 v137, v137, v89
	v_cvt_pk_bf16_f32 v137, v137, v137
	global_store_short v[110:111], v137, off offset:768
	v_add_f32_e32 v138, v6, v66
	v_lshlrev_b32_e32 v90, 16, v90
	v_mul_f32_e32 v138, v138, v90
	v_cvt_pk_bf16_f32 v138, v138, v138
	global_store_short v[112:113], v138, off offset:768
	v_add_f32_e32 v139, v7, v67
	v_lshlrev_b32_e32 v91, 16, v91
	v_mul_f32_e32 v139, v139, v91
	v_cvt_pk_bf16_f32 v139, v139, v139
	global_store_short v[114:115], v139, off offset:768
	v_add_f32_e32 v140, v8, v68
	v_lshlrev_b32_e32 v92, 16, v92
	v_mul_f32_e32 v140, v140, v92
	v_cvt_pk_bf16_f32 v140, v140, v140
	global_store_short v[116:117], v140, off offset:768
	v_add_f32_e32 v141, v9, v69
	v_lshlrev_b32_e32 v93, 16, v93
	v_mul_f32_e32 v141, v141, v93
	v_cvt_pk_bf16_f32 v141, v141, v141
	global_store_short v[118:119], v141, off offset:768
	v_add_f32_e32 v142, v10, v70
	v_lshlrev_b32_e32 v94, 16, v94
	v_mul_f32_e32 v142, v142, v94
	v_cvt_pk_bf16_f32 v142, v142, v142
	global_store_short v[120:121], v142, off offset:768
	v_add_f32_e32 v143, v11, v71
	v_lshlrev_b32_e32 v95, 16, v95
	v_mul_f32_e32 v143, v143, v95
	v_cvt_pk_bf16_f32 v143, v143, v143
	global_store_short v[122:123], v143, off offset:768
	v_add_f32_e32 v144, v12, v72
	v_lshlrev_b32_e32 v96, 16, v96
	v_mul_f32_e32 v144, v144, v96
	v_cvt_pk_bf16_f32 v144, v144, v144
	global_store_short v[124:125], v144, off offset:768
	v_add_f32_e32 v145, v13, v73
	v_lshlrev_b32_e32 v97, 16, v97
	v_mul_f32_e32 v145, v145, v97
	v_cvt_pk_bf16_f32 v145, v145, v145
	global_store_short v[126:127], v145, off offset:768
	v_add_f32_e32 v146, v14, v74
	v_lshlrev_b32_e32 v98, 16, v98
	v_mul_f32_e32 v146, v146, v98
	v_cvt_pk_bf16_f32 v146, v146, v146
	global_store_short v[128:129], v146, off offset:768
	v_add_f32_e32 v147, v15, v75
	v_lshlrev_b32_e32 v99, 16, v99
	v_mul_f32_e32 v147, v147, v99
	v_cvt_pk_bf16_f32 v147, v147, v147
	global_store_short v[130:131], v147, off offset:768
	v_or_b32_e32 v194, 27, v194
	s_barrier
	s_mov_b64 s[0:1], 0
